# MF per-lane next-mixer constants: 14 loads issued together with one wait (was four load/wait groups); on top of v24
# speedup vs baseline: 1.0019x; 1.0019x over previous
; __device__ __forceinline__ void phase_mf(const Params& p, Frame& F, int l, const bool dry) {
;     ...
;     const float* mod = (const float*)(p.ws + WS_MOD) + (size_t)l * NB * 6 * D;
;     const bool nxt = (l + 1 < DEPTH);
;     const float* modn = mod + NB * 6 * D; const float* gainn = (const float*)(p.ws + WS_PAR) + PAR_NMIX + (l + 1) * D;
;     const int gw = F.vcu * NWAVES + F.wave, NGW = F.G * NWAVES;
;     const int b = (gw * 2) / NGW, wsub = gw - b * (NGW / 2), nsub = NGW / 2;
;     const bool xmap = (nsub == 1024); const int rb0 = xmap ? ((wsub >> 8) << 11) + (wsub & 255) : wsub, rstep = xmap ? 256 : nsub;
;     f32x4 g2v[2][2], Anv[2][2], Bnv[2][2];
; #pragma unroll
;     for (int j = 0; j < 2; ++j) { const int c0 = 512 * j + 8 * F.lane; const f32x4* gp = (const f32x4*)(mod + b * 6 * D + 5 * D + c0); g2v[j][0] = gp[0]; g2v[j][1] = gp[1];
; #pragma unroll
;         for (int hf = 0; hf < 2; ++hf) { if (nxt) { const f32x4 gn = *(const f32x4*)(gainn + c0 + 4 * hf), sn = *(const f32x4*)(modn + b * 6 * D + 1 * D + c0 + 4 * hf); Anv[j][hf] = gn * (sn + 1.0f); Bnv[j][hf] = *(const f32x4*)(modn + b * 6 * D + c0 + 4 * hf); }
;             else { Anv[j][hf] = (f32x4){0.f, 0.f, 0.f, 0.f}; Bnv[j][hf] = Anv[j][hf]; } } }
.LBB0_1427:
	v_readlane_b32 s2, v251, 9
	v_readlane_b32 s3, v251, 10
	s_cmp_le_i32 s2, s16
	s_cselect_b64 s[0:1], -1, 0
	s_cmp_lt_i32 s16, s3
	s_cselect_b64 s[2:3], -1, 0
	s_and_b64 s[0:1], s[0:1], s[2:3]
	s_andn2_b64 vcc, exec, s[0:1]
	s_cbranch_vccnz .LBB0_176
	v_readlane_b32 s2, v254, 45
	v_readlane_b32 s8, v251, 0
	s_cmp_lg_u32 s2, 3
	v_readlane_b32 s6, v251, 14
	v_readlane_b32 s10, v251, 2
	v_readlane_b32 s11, v251, 3
	s_mul_i32 s4, s2, 0xc000
	s_cselect_b64 s[0:1], -1, 0
	s_lshl_b32 s34, s2, 10
	v_readlane_b32 s7, v251, 15
	v_readlane_b32 s9, v251, 1
	s_mov_b64 s[2:3], s[10:11]
	s_add_u32 s9, s6, s4
	s_addc_u32 s14, s7, 0
	s_lshl_b64 s[4:5], s[34:35], 2
	v_readlane_b32 s8, v251, 13
	s_add_u32 s10, s6, s4
	v_readlane_b32 s4, v251, 26
	s_addc_u32 s11, s7, s5
	s_add_i32 s4, s8, s4
	s_lshl_b32 s5, s4, 1
	s_ashr_i32 s8, s5, 31
	v_readlane_b32 s12, v253, 45
	s_xor_b32 s8, s8, s12
	s_abs_i32 s5, s5
	v_readlane_b32 s12, v253, 40
	s_mul_hi_u32 s12, s5, s12
	v_readlane_b32 s16, v253, 39
	s_mul_i32 s13, s12, s16
	s_sub_i32 s5, s5, s13
	s_add_i32 s13, s12, 1
	s_sub_i32 s15, s5, s16
	s_cmp_ge_u32 s5, s16
	s_cselect_b32 s12, s13, s12
	s_cselect_b32 s5, s15, s5
	s_add_i32 s13, s12, 1
	s_cmp_ge_u32 s5, s16
	s_cselect_b32 s5, s13, s12
	s_xor_b32 s5, s5, s8
	s_sub_i32 s8, s5, s8
	s_mul_i32 s12, s8, 0x1800
	s_ashr_i32 s13, s12, 31
	s_waitcnt vmcnt(0) lgkmcnt(0)
	v_mbcnt_lo_u32_b32 v56, -1, 0
	v_mbcnt_hi_u32_b32 v56, -1, v56
	s_lshl_b64 s[12:13], s[12:13], 2
	v_lshlrev_b32_e32 v58, 3, v56
	s_add_u32 s12, s9, s12
	v_ashrrev_i32_e32 v59, 31, v58
	s_addc_u32 s13, s14, s13
	v_lshlrev_b64 v[8:9], 2, v[58:59]
	v_lshl_add_u64 v[10:11], s[12:13], 0, v[8:9]
	v_add_co_u32_e32 v0, vcc, 0x105000, v10
	s_mov_b64 s[12:13], 0x105000
	s_nop 0
	v_addc_co_u32_e32 v1, vcc, 0, v11, vcc
	v_lshl_add_u64 v[20:21], v[10:11], 0, s[12:13]
	flat_load_dwordx4 v[0:3], v[0:1]
	s_nop 0
	flat_load_dwordx4 v[4:7], v[20:21] offset:16
	v_lshl_add_u64 v[8:9], s[10:11], 0, v[8:9]
	s_mov_b64 s[10:11], 0x2401000
	v_lshl_add_u64 v[36:37], v[8:9], 0, s[10:11]
	s_mov_b64 s[10:11], 0x10d000
	v_lshl_add_u64 v[34:35], v[10:11], 0, s[10:11]
	s_mov_b64 s[10:11], 0x10c000
	v_lshl_add_u64 v[32:33], v[10:11], 0, s[10:11]
	v_mov_b32_e32 v60, 0
	s_and_b64 vcc, exec, s[0:1]
	v_mov_b32_e32 v62, 0
	v_mov_b32_e32 v63, 0
	v_mov_b32_e32 v64, 0
	v_mov_b32_e32 v65, 0
	v_mov_b32_e32 v8, 0
	v_mov_b32_e32 v9, 0
	v_mov_b32_e32 v10, 0
	v_mov_b32_e32 v11, 0
	s_cbranch_vccz .LBB0_1430
	global_load_dwordx4 v[76:79], v[36:37], off
	global_load_dwordx4 v[80:83], v[34:35], off
	global_load_dwordx4 v[84:87], v[36:37], off offset:16
	global_load_dwordx4 v[88:91], v[34:35], off offset:16
	global_load_dwordx4 v[92:95], v[36:37], off offset:2048
	global_load_dwordx4 v[96:99], v[34:35], off offset:2048
	global_load_dwordx4 v[100:103], v[36:37], off offset:2064
	global_load_dwordx4 v[104:107], v[34:35], off offset:2064
	global_load_dwordx4 v[8:11], v[32:33], off
	global_load_dwordx4 v[12:15], v[32:33], off offset:16
	global_load_dwordx4 v[24:27], v[32:33], off offset:2048
	global_load_dwordx4 v[28:31], v[32:33], off offset:2064
	global_load_dwordx4 v[16:19], v[20:21], off offset:2048
	s_nop 0
	global_load_dwordx4 v[20:23], v[20:21], off offset:2064
	s_mov_b64 s[36:37], 0
	s_waitcnt vmcnt(0) lgkmcnt(0)
	v_pk_add_f32 v[82:83], v[82:83], 1.0 op_sel_hi:[1,0]
	v_pk_add_f32 v[80:81], v[80:81], 1.0 op_sel_hi:[1,0]
	v_pk_mul_f32 v[64:65], v[78:79], v[82:83]
	v_pk_mul_f32 v[62:63], v[76:77], v[80:81]
	v_pk_add_f32 v[90:91], v[90:91], 1.0 op_sel_hi:[1,0]
	v_pk_add_f32 v[88:89], v[88:89], 1.0 op_sel_hi:[1,0]
	v_pk_mul_f32 v[66:67], v[86:87], v[90:91]
	v_pk_mul_f32 v[60:61], v[84:85], v[88:89]
	v_pk_add_f32 v[98:99], v[98:99], 1.0 op_sel_hi:[1,0]
	v_pk_add_f32 v[96:97], v[96:97], 1.0 op_sel_hi:[1,0]
	v_pk_mul_f32 v[72:73], v[94:95], v[98:99]
	v_pk_mul_f32 v[70:71], v[92:93], v[96:97]
	v_pk_add_f32 v[106:107], v[106:107], 1.0 op_sel_hi:[1,0]
	v_pk_add_f32 v[104:105], v[104:105], 1.0 op_sel_hi:[1,0]
	v_pk_mul_f32 v[74:75], v[102:103], v[106:107]
	v_pk_mul_f32 v[68:69], v[100:101], v[104:105]
	s_branch .LBB0_1436
	flat_load_dwordx4 v[8:11], v[36:37]
	flat_load_dwordx4 v[12:15], v[34:35]
	s_waitcnt vmcnt(0) lgkmcnt(0)
	v_pk_add_f32 v[14:15], v[14:15], 1.0 op_sel_hi:[1,0]
	v_pk_add_f32 v[12:13], v[12:13], 1.0 op_sel_hi:[1,0]
	v_pk_mul_f32 v[64:65], v[10:11], v[14:15]
	v_pk_mul_f32 v[62:63], v[8:9], v[12:13]
	flat_load_dwordx4 v[8:11], v[32:33]
